# phase D task remap for XCD locality: the 17 s5 tasks of a group and the 4 N-tiles of an fnet M-tile land on one shard (same XCD L2)
# speedup vs baseline: 1.0107x; 1.0078x over previous
.LBB0_296:
	s_cmpk_lt_i32 s14, 0x220
	s_cbranch_scc1 .Ldloc_fnet
	s_cmpk_ge_i32 s14, 0x440
	s_cbranch_scc1 .Ldloc_done
	s_addk_i32 s14, 0xfde0
	s_and_b32 s98, s14, 7
	s_lshr_b32 s14, s14, 3
	s_mul_i32 s98, s98, 68
	s_add_i32 s14, s14, s98
	s_addk_i32 s14, 0x220
	s_branch .Ldloc_done
.Ldloc_fnet:
	s_and_b32 s98, s14, 7
	s_lshr_b32 s99, s14, 3
	s_and_b32 s14, s99, 3
	s_lshr_b32 s99, s99, 2
	s_lshl_b32 s99, s99, 5
	s_lshl_b32 s98, s98, 2
	s_add_i32 s14, s14, s98
	s_add_i32 s14, s14, s99
